# prompt attention software-pipelined (A waves: QK/softmax/PV interleaved as the baseline step; B waves: all LDS-DMA staging + PV of the second value half two iterations behind)
# speedup vs baseline: 1.0617x; 1.0082x over previous
; template<int THRL,bool PART> __device__ __forceinline__ int attn_unit(const bf16*Qb,const bf16*__restrict__ Kh,const bf16*__restrict__ Vh,bf16*Ob,const int NT,const int vlim_in,char*shm,const int s0,const bool primed,const bf16*nKh,const bf16*nVh,bf16*fuseM,const float lam){
;     ...
;   const int lane=tid&63,r32=lane&31,hi=lane>>5; const int wid=__builtin_amdgcn_readfirstlane(tid>>6);
;   const int vlim=(vlim_in<0)?(wid>>1):vlim_in;
;   const bool act=PART?(wid<2):true;
;   const bf16*Qw=Qb+(long)(wid*QBLK)*KP;
;   const unsigned lds0=(unsigned)(uintptr_t)shm;
;   float*wsf=(float*)(shm+LDS_WS)+wid*64;
;   const bf16*ksrc=Kh+(long)lane*KP+wid*8;
;   const bf16*vsrc=Vh+(long)(16*(wid&3)+(lane>>2))*KP+(wid>>2)*32+(lane&3)*8;
;   const unsigned kdst=lds0+LDS_K+wid*1024, vdst=lds0+LDS_V+wid*1024;
;     ...
;   const int vb0=(int)(lds0+LDS_V)+((lane>>4)&1)*32+(lane&3)*8+(4*hi+((lane&15)>>2))*64;
;   const int s1=(s0==(NSLOT-1)*SLOTB)?0:s0+SLOTB, s2=(s1==(NSLOT-1)*SLOTB)?0:s1+SLOTB;
;   const char*Kbase=shm+LDS_K+s0; bf16x8 kf[8];
;   const lds_cptr shm3=(lds_cptr)shm; const lds_cptr kp0=shm3+LDS_K+hi*1024+r32*16; const lds_cptr vp0=shm3+LDS_V+((lane>>4)&1)*32+(lane&3)*8+(4*hi+((lane&15)>>2))*64;
.LBB0_925:
	s_cmpk_gt_i32 s92, 0xff
	s_waitcnt vmcnt(0) lgkmcnt(0)
	s_barrier
	s_cbranch_scc1 .LBB0_1021
	v_mov_b32_e32 v3, 0x1a0000
	global_load_dword v216, v3, s[66:67]
	v_and_b32_e32 v0, 63, v252
	v_and_b32_e32 v1, 31, v252
	v_bfe_u32 v2, v252, 5, 1
	v_lshrrev_b32_e32 v3, 6, v252
	s_nop 0
	v_readfirstlane_b32 s4, v3
	s_and_b32 s5, s4, 3
	s_lshr_b32 s6, s4, 2
	s_mov_b32 s48, 0x41000000
	v_lshlrev_b32_e32 v232, 10, v2
	v_lshl_add_u32 v232, v1, 4, v232
	v_bfe_u32 v217, v0, 4, 1
	v_lshlrev_b32_e32 v233, 5, v217
	v_and_b32_e32 v217, 3, v0
	v_lshl_add_u32 v233, v217, 3, v233
	v_bfe_u32 v217, v0, 2, 2
	v_lshl_add_u32 v217, v2, 2, v217
	v_lshl_add_u32 v233, v217, 6, v233
	s_lshl_b32 s34, s6, 13
	v_add_u32_e32 v233, s34, v233
	s_lshl_b32 s34, s5, 12
	s_add_i32 s34, s34, 0x16000
	v_lshlrev_b32_e32 v234, 4, v0
	v_lshlrev_b32_e32 v242, 4, v0
	v_add_u32_e32 v244, 0x1000, v242
	v_add_u32_e32 v234, s34, v234
	s_lshl_b32 s34, s5, 10
	s_add_i32 s34, s34, 0x1e000
	v_mov_b32_e32 v235, s34
	v_lshlrev_b32_e32 v240, 2, v1
	v_lshlrev_b32_e32 v241, 4, v2
	s_lshl_b32 s34, s5, 4
	v_lshlrev_b32_e32 v236, 10, v0
	v_add_u32_e32 v236, s34, v236
	v_lshrrev_b32_e32 v217, 2, v0
	v_lshlrev_b32_e32 v237, 10, v217
	v_and_b32_e32 v217, 3, v0
	v_lshl_add_u32 v237, v217, 4, v237
	s_lshl_b32 s34, s5, 14
	v_add_u32_e32 v237, s34, v237
	v_lshlrev_b32_e32 v239, 10, v1
	v_lshl_add_u32 v239, v2, 4, v239
	s_lshl_b32 s34, s92, 3
	s_add_i32 s34, s34, s4
	s_lshl_b32 s34, s34, 13
	s_add_u32 s52, s66, s34
	s_addc_u32 s53, s67, 0
	s_add_u32 s52, s52, 0x6f00000
	s_addc_u32 s53, s53, 0
	s_waitcnt vmcnt(0)
	v_readfirstlane_b32 s7, v216
	s_mov_b32 s8, s92

; #define WAIT_BAR(N) asm volatile("s_waitcnt vmcnt(" #N ") lgkmcnt(0)\n\ts_barrier":::"memory")
;   #define DMA_K(t,slot) glds16(ksrc+(long)(t)*KVBLK*KP,(unsigned)__builtin_amdgcn_readfirstlane(kdst+(slot)))
;   #define DMA_V(t,slot) glds16(vsrc+(long)(t)*KVBLK*KP,(unsigned)__builtin_amdgcn_readfirstlane(vdst+(slot)))
;   #define CMASK(P0,P1,t) do{int jb_=(t)-(NT-4); if(jb_>=0)cmask(P0,P1,jb_,vlim);}while(0)
;   #define CMASK(P0,P1,t) do{}while(0)
; template<int THRL,bool PART> __device__ __forceinline__ int attn_unit(const bf16*Qb,const bf16*__restrict__ Kh,const bf16*__restrict__ Vh,bf16*Ob,const int NT,const int vlim_in,char*shm,const int s0,const bool primed,const bf16*nKh,const bf16*nVh,bf16*fuseM,const float lam){
;     ...
;   const bf16*Qw=Qb+(long)(wid*QBLK)*KP;
;   const unsigned lds0=(unsigned)(uintptr_t)shm;
;   float*wsf=(float*)(shm+LDS_WS)+wid*64;
;   const bf16*ksrc=Kh+(long)lane*KP+wid*8;
;   const bf16*vsrc=Vh+(long)(16*(wid&3)+(lane>>2))*KP+(wid>>2)*32+(lane&3)*8;
;   const unsigned kdst=lds0+LDS_K+wid*1024, vdst=lds0+LDS_V+wid*1024;
;     ...
;   const int vb0=(int)(lds0+LDS_V)+((lane>>4)&1)*32+(lane&3)*8+(4*hi+((lane&15)>>2))*64;
;   const int s1=(s0==(NSLOT-1)*SLOTB)?0:s0+SLOTB, s2=(s1==(NSLOT-1)*SLOTB)?0:s1+SLOTB;
;   const char*Kbase=shm+LDS_K+s0; bf16x8 kf[8];
;   const lds_cptr shm3=(lds_cptr)shm; const lds_cptr kp0=shm3+LDS_K+hi*1024+r32*16; const lds_cptr vp0=shm3+LDS_V+((lane>>4)&1)*32+(lane&3)*8+(4*hi+((lane&15)>>2))*64;
;   if(!primed){DMA_K(0,s0);DMA_V(0,s0);DMA_K(1,s1);}
;   bf16x8 qr[4];
;   #pragma unroll
;   for(int d0=0;d0<4;++d0)qr[d0]=*reinterpret_cast<const bf16x8*>(&Qw[(long)r32*KP+d0*16+hi*8]);
;   float zz_=0.f;asm volatile("":"+v"(zz_));
;   float mhat=zz_,l_reg=zz_;f32x16 o[2];
;   _Pragma("unroll") for(int r=0;r<16;++r){o[0][r]=zz_;o[1][r]=zz_;}
;   f32x16 negm;
;   _Pragma("unroll") for(int r=0;r<16;++r)negm[r]=zz_;
;   asm volatile("":"+v"(negm));
;     ...
;   bool resc=false;
;     ...
;   f32x16 pA0,pA1,pB0,pB1;
;   int sl_prev=s0,sl_cur=s0,sl_next=s1;
;     ...
;   if(!primed){DMA_K(2,s2);}
;   WAIT_BAR(3);
;   if(act){
;   qkt(pA0,pA1,Kbase,qr,negm,r32,hi);asm volatile("s_nop 15\n\ts_nop 7":"+v"(pA0),"+v"(pA1));CMASK(pA0,pA1,0);
;   START(pA0,pA1);
;   _Pragma("unroll") for(int r=0;r<16;++r)pA1[r]=__builtin_amdgcn_exp2f(pA1[r]);
;   }
;   WAIT_BAR(0);
;   DMA_K(3,s0);DMA_V(1,s1);
;   ROT();
;   if(act)kload8(kf,kp0+sl_cur);
;   WAIT_BAR(2);
.Lat_j:
	s_lshl_b32 s34, s10, 1
	s_add_i32 s34, s34, s14
	s_add_u32 s18, s66, 0xf300000
	s_addc_u32 s19, s67, 0
	s_lshl_b32 s36, s9, 22
	s_add_u32 s18, s18, s36
	s_addc_u32 s19, s19, 0
	s_lshl_b32 s36, s34, 7
	s_add_u32 s18, s18, s36
	s_addc_u32 s19, s19, 0
	s_add_u32 s20, s66, 0x12200000
	s_addc_u32 s21, s67, 0
	s_lshl_b32 s36, s9, 22
	s_add_u32 s20, s20, s36
	s_addc_u32 s21, s21, 0
	s_lshl_b32 s36, s10, 8
	s_add_u32 s20, s20, s36
	s_addc_u32 s21, s21, 0
	s_add_u32 s22, s66, 0xd100000
	s_addc_u32 s23, s67, 0
	s_lshl_b32 s36, s9, 22
	s_add_u32 s22, s22, s36
	s_addc_u32 s23, s23, 0
	s_lshl_b32 s36, s13, 17
	s_add_u32 s22, s22, s36
	s_addc_u32 s23, s23, 0
	s_lshl_b32 s36, s5, 15
	s_add_u32 s22, s22, s36
	s_addc_u32 s23, s23, 0
	s_lshl_b32 s36, s34, 7
	s_add_u32 s22, s22, s36
	s_addc_u32 s23, s23, 0
	s_mov_b32 s17, 0
	s_mov_b32 s24, 0
	s_mov_b32 s25, 0
	s_cmp_lg_u32 s6, 0
	s_cbranch_scc1 .Lat_prob2
	global_load_dwordx4 v[4:7], v239, s[22:23]
	global_load_dwordx4 v[8:11], v239, s[22:23] offset:32
	global_load_dwordx4 v[12:15], v239, s[22:23] offset:64
	global_load_dwordx4 v[16:19], v239, s[22:23] offset:96
	s_branch .Lat_noq1
.Lat_prob2:
	s_mov_b32 s27, 0
	s_lshl_b32 s37, s5, 10
	s_add_i32 m0, s37, s27
	s_add_u32 s38, s18, 64
	s_addc_u32 s39, s19, 0
	global_load_lds_dwordx4 v236, s[18:19]
	s_add_i32 m0, m0, 0x1000
	s_nop 0
	global_load_lds_dwordx4 v236, s[38:39]
	s_add_u32 s18, s18, 0x10000
	s_addc_u32 s19, s19, 0
	s_mov_b32 s27, 0x2000
	s_lshl_b32 s37, s5, 10
	s_add_i32 m0, s37, s27
	s_add_u32 s38, s18, 64
	s_addc_u32 s39, s19, 0
	global_load_lds_dwordx4 v236, s[18:19]
	s_add_i32 m0, m0, 0x1000
	s_nop 0
	global_load_lds_dwordx4 v236, s[38:39]
	s_add_u32 s18, s18, 0x10000
	s_addc_u32 s19, s19, 0
	s_cmp_gt_u32 s15, 2
	s_cbranch_scc0 .Lat_nok23
	s_mov_b32 s27, 0x4000
	s_lshl_b32 s37, s5, 10
	s_add_i32 m0, s37, s27
	s_add_u32 s38, s18, 64
	s_addc_u32 s39, s19, 0
	global_load_lds_dwordx4 v236, s[18:19]
	s_add_i32 m0, m0, 0x1000
	s_nop 0
	global_load_lds_dwordx4 v236, s[38:39]
	s_add_u32 s18, s18, 0x10000
	s_addc_u32 s19, s19, 0
.Lat_nok23:
	s_mov_b32 s30, 0x6000
	s_lshl_b32 s37, s5, 10
	s_add_i32 m0, s37, s30
	s_mov_b64 s[38:39], s[20:21]
	global_load_lds_dwordx4 v237, s[38:39]
	s_add_i32 m0, m0, 0x1000
	s_add_u32 s38, s38, 64
	s_addc_u32 s39, s39, 0
	global_load_lds_dwordx4 v237, s[38:39]
	s_add_i32 m0, m0, 0x1000
	s_add_u32 s38, s38, 64
	s_addc_u32 s39, s39, 0
	global_load_lds_dwordx4 v237, s[38:39]
	s_add_i32 m0, m0, 0x1000
	s_add_u32 s38, s38, 64
	s_addc_u32 s39, s39, 0
	global_load_lds_dwordx4 v237, s[38:39]
	s_add_u32 s20, s20, 0x10000
	s_addc_u32 s21, s21, 0
.Lat_noq1:
	v_mov_b32_e32 v148, 0
	v_mov_b32_e32 v149, 0
	v_mov_b32_e32 v150, 0
	v_mov_b32_e32 v151, 0
	v_mov_b32_e32 v152, 0
	v_mov_b32_e32 v153, 0
	v_mov_b32_e32 v154, 0
	v_mov_b32_e32 v155, 0
	v_mov_b32_e32 v156, 0
	v_mov_b32_e32 v157, 0
	v_mov_b32_e32 v158, 0
	v_mov_b32_e32 v159, 0
	v_mov_b32_e32 v160, 0
	v_mov_b32_e32 v161, 0
	v_mov_b32_e32 v162, 0
	v_mov_b32_e32 v163, 0
	v_mov_b32_e32 v164, 0
	v_mov_b32_e32 v165, 0
	v_mov_b32_e32 v166, 0
	v_mov_b32_e32 v167, 0
	v_mov_b32_e32 v168, 0
	v_mov_b32_e32 v169, 0
	v_mov_b32_e32 v170, 0
	v_mov_b32_e32 v171, 0
	v_mov_b32_e32 v172, 0
	v_mov_b32_e32 v173, 0
	v_mov_b32_e32 v174, 0
	v_mov_b32_e32 v175, 0
	v_mov_b32_e32 v176, 0
	v_mov_b32_e32 v177, 0
	v_mov_b32_e32 v178, 0
	v_mov_b32_e32 v179, 0
	v_mov_b32_e32 v84, 0
	v_mov_b32_e32 v85, 0
	v_mov_b32_e32 v86, 0
	v_mov_b32_e32 v87, 0
	v_mov_b32_e32 v88, 0
	v_mov_b32_e32 v89, 0
	v_mov_b32_e32 v90, 0
	v_mov_b32_e32 v91, 0
	v_mov_b32_e32 v92, 0
	v_mov_b32_e32 v93, 0
	v_mov_b32_e32 v94, 0
	v_mov_b32_e32 v95, 0
	v_mov_b32_e32 v96, 0
	v_mov_b32_e32 v97, 0
	v_mov_b32_e32 v98, 0
	v_mov_b32_e32 v99, 0
	v_mov_b32_e32 v212, 0
	v_mov_b32_e32 v213, 0
	s_waitcnt vmcnt(0)
	s_barrier
	s_cmp_lg_u32 s6, 0
	s_cbranch_scc1 .Lat_nokf4
	v_mov_b32_e32 v216, v232
	ds_read_b128 v[20:23], v216 offset:0
	ds_read_b128 v[24:27], v216 offset:512
	ds_read_b128 v[28:31], v216 offset:2048
	ds_read_b128 v[32:35], v216 offset:2560
	ds_read_b128 v[36:39], v216 offset:4096
	ds_read_b128 v[40:43], v216 offset:4608
	ds_read_b128 v[44:47], v216 offset:6144
	ds_read_b128 v[48:51], v216 offset:6656
.Lat_nokf4:
.Lat_t5:
	s_add_i32 s26, s24, 1
	s_cmp_ge_u32 s26, 3
	s_cselect_b32 s35, 3, 0
	s_sub_i32 s26, s26, s35
	s_lshl_b32 s26, s26, 13
	s_lshl_b32 s27, s24, 13
	s_add_i32 s28, s25, 3
	s_and_b32 s28, s28, 3
	s_lshl_b32 s28, s28, 14
	s_add_i32 s28, s28, 0x6000
	s_add_i32 s29, s25, 2
	s_and_b32 s29, s29, 3
	s_lshl_b32 s29, s29, 14
	s_add_i32 s29, s29, 0x6000
	s_add_i32 s30, s25, 1
	s_and_b32 s30, s30, 3
	s_lshl_b32 s30, s30, 14
	s_add_i32 s30, s30, 0x6000
	s_and_b32 s34, s17, 1
	s_lshl_b32 s32, s34, 14
	s_xor_b32 s31, s32, 0x4000
	s_lshl_b32 s44, s34, 7
	s_xor_b32 s45, s44, 0x80
	s_lshl_b32 s46, s34, 2
	s_xor_b32 s47, s46, 4
	s_cmp_lg_u32 s6, 0
	s_cbranch_scc1 .Lat_B7
	s_cmp_lt_u32 s17, s16
	s_cbranch_scc0 .Lat_Alast12
	s_cmp_eq_u32 s17, 0
	s_cbranch_scc1 .Lat_Afirst10
.Lat_Asteady11:
	v_add_u32_e32 v217, s28, v233
	v_add_u32_e32 v222, s31, v234
	s_waitcnt lgkmcnt(0)
	ds_read_b64_tr_b16 v[116:117], v217 offset:0
	ds_read_b64_tr_b16 v[118:119], v217 offset:512
	v_mfma_f32_32x32x16_bf16 v[52:67], v[20:23], v[4:7], v[84:99]
	v_add_f32_e32 v243, v180, v181
	v_add_f32_e32 v243, v243, v182
	v_add_f32_e32 v243, v243, v183
	v_add_f32_e32 v243, v243, v184
	v_add_f32_e32 v243, v243, v185
	v_cvt_pk_bf16_f32 v100, v180, v181
	v_cvt_pk_bf16_f32 v101, v182, v183
	ds_read_b64_tr_b16 v[132:133], v217 offset:4096
	ds_read_b64_tr_b16 v[134:135], v217 offset:4608
	v_mfma_f32_32x32x16_bf16 v[68:83], v[24:27], v[4:7], v[84:99]
	v_add_f32_e32 v243, v243, v186
	v_add_f32_e32 v243, v243, v187
	v_add_f32_e32 v243, v243, v188
	v_add_f32_e32 v243, v243, v189
	v_cvt_pk_bf16_f32 v102, v184, v185
	v_cvt_pk_bf16_f32 v103, v186, v187
	ds_write_b128 v222, v[100:103] offset:0
	ds_read_b64_tr_b16 v[120:121], v217 offset:1024
	ds_read_b64_tr_b16 v[122:123], v217 offset:1536
	v_mfma_f32_32x32x16_bf16 v[52:67], v[28:31], v[8:11], v[52:67]
	v_add_f32_e32 v243, v243, v190
	v_add_f32_e32 v243, v243, v191
	v_add_f32_e32 v243, v243, v192
	v_add_f32_e32 v243, v243, v193
	v_cvt_pk_bf16_f32 v104, v188, v189
	v_cvt_pk_bf16_f32 v105, v190, v191
	ds_read_b64_tr_b16 v[136:137], v217 offset:5120
	ds_read_b64_tr_b16 v[138:139], v217 offset:5632
	v_mfma_f32_32x32x16_bf16 v[68:83], v[32:35], v[8:11], v[68:83]
	v_add_f32_e32 v243, v243, v194
	v_add_f32_e32 v243, v243, v195
	v_add_f32_e32 v243, v243, v196
	v_add_f32_e32 v243, v243, v197
	v_cvt_pk_bf16_f32 v106, v192, v193
	v_cvt_pk_bf16_f32 v107, v194, v195
	ds_write_b128 v222, v[104:107] offset:1024
	ds_read_b64_tr_b16 v[124:125], v217 offset:2048
	ds_read_b64_tr_b16 v[126:127], v217 offset:2560
	v_mfma_f32_32x32x16_bf16 v[52:67], v[36:39], v[12:15], v[52:67]
	v_add_f32_e32 v243, v243, v198
	v_add_f32_e32 v243, v243, v199
	v_add_f32_e32 v243, v243, v200
	v_add_f32_e32 v243, v243, v201
	v_cvt_pk_bf16_f32 v108, v196, v197
	v_cvt_pk_bf16_f32 v109, v198, v199
	ds_read_b64_tr_b16 v[140:141], v217 offset:6144
	ds_read_b64_tr_b16 v[142:143], v217 offset:6656
	v_mfma_f32_32x32x16_bf16 v[68:83], v[40:43], v[12:15], v[68:83]
	v_add_f32_e32 v243, v243, v202
	v_add_f32_e32 v243, v243, v203
	v_add_f32_e32 v243, v243, v204
	v_add_f32_e32 v243, v243, v205
	v_cvt_pk_bf16_f32 v110, v200, v201
	v_cvt_pk_bf16_f32 v111, v202, v203
	ds_write_b128 v222, v[108:111] offset:2048
	ds_read_b64_tr_b16 v[128:129], v217 offset:3072
	ds_read_b64_tr_b16 v[130:131], v217 offset:3584
	v_mfma_f32_32x32x16_bf16 v[52:67], v[44:47], v[16:19], v[52:67]
	v_add_f32_e32 v243, v243, v206
	v_add_f32_e32 v243, v243, v207
	v_add_f32_e32 v243, v243, v208
	v_add_f32_e32 v243, v243, v209
	v_cvt_pk_bf16_f32 v112, v204, v205
	v_cvt_pk_bf16_f32 v113, v206, v207
	ds_read_b64_tr_b16 v[144:145], v217 offset:7168
	ds_read_b64_tr_b16 v[146:147], v217 offset:7680
	v_mfma_f32_32x32x16_bf16 v[68:83], v[48:51], v[16:19], v[68:83]
	v_add_f32_e32 v243, v243, v210
	v_add_f32_e32 v243, v243, v211
	v_cvt_pk_bf16_f32 v114, v208, v209
	v_cvt_pk_bf16_f32 v115, v210, v211
	ds_write_b128 v222, v[112:115] offset:3072
	v_add_f32_e32 v213, v213, v243
	s_nop 4
	v_max3_f32 v218, v52, v53, v54
	v_max3_f32 v219, v55, v56, v57
	v_max3_f32 v218, v218, v58, v59
	v_max3_f32 v219, v219, v60, v61
	v_max3_f32 v218, v218, v62, v63
	v_max3_f32 v219, v219, v64, v65
	v_max3_f32 v218, v218, v66, v67
	v_max3_f32 v219, v219, v68, v69
	v_max3_f32 v218, v218, v70, v71
	v_max3_f32 v219, v219, v72, v73
	v_max3_f32 v218, v218, v74, v75
	v_max3_f32 v219, v219, v76, v77
	v_max3_f32 v218, v218, v78, v79
	v_max3_f32 v219, v219, v80, v81
	v_max3_f32 v218, v218, v82, v83
	v_max_f32_e32 v214, v218, v219
	v_mov_b32_e32 v218, v214
	s_nop 1
	v_permlane32_swap_b32_e32 v214, v218
	v_max_f32_e32 v214, v214, v218
	s_mov_b32 s54, 0
	v_mov_b32_e32 v220, 0
	v_cmp_lt_f32_e32 vcc, s48, v214
	s_nop 0
	s_cmp_lg_u64 vcc, 0
	s_cbranch_scc0 .Lat_nores14
	v_max_f32_e32 v214, 0, v214
	v_add_f32_e32 v212, v212, v214
	v_sub_f32_e32 v52, v52, v214
	v_sub_f32_e32 v53, v53, v214
	v_sub_f32_e32 v54, v54, v214
	v_sub_f32_e32 v55, v55, v214
	v_sub_f32_e32 v56, v56, v214
	v_sub_f32_e32 v57, v57, v214
	v_sub_f32_e32 v58, v58, v214
	v_sub_f32_e32 v59, v59, v214
	v_sub_f32_e32 v60, v60, v214
	v_sub_f32_e32 v61, v61, v214
	v_sub_f32_e32 v62, v62, v214
	v_sub_f32_e32 v63, v63, v214
	v_sub_f32_e32 v64, v64, v214
	v_sub_f32_e32 v65, v65, v214
	v_sub_f32_e32 v66, v66, v214
	v_sub_f32_e32 v67, v67, v214
	v_sub_f32_e32 v68, v68, v214
	v_sub_f32_e32 v69, v69, v214
	v_sub_f32_e32 v70, v70, v214
	v_sub_f32_e32 v71, v71, v214
	v_sub_f32_e32 v72, v72, v214
	v_sub_f32_e32 v73, v73, v214
	v_sub_f32_e32 v74, v74, v214
	v_sub_f32_e32 v75, v75, v214
	v_sub_f32_e32 v76, v76, v214
	v_sub_f32_e32 v77, v77, v214
	v_sub_f32_e32 v78, v78, v214
	v_sub_f32_e32 v79, v79, v214
	v_sub_f32_e32 v80, v80, v214
	v_sub_f32_e32 v81, v81, v214
	v_sub_f32_e32 v82, v82, v214
	v_sub_f32_e32 v83, v83, v214
	v_xor_b32_e32 v84, 0x80000000, v212
	v_xor_b32_e32 v85, 0x80000000, v212
	v_xor_b32_e32 v86, 0x80000000, v212
	v_xor_b32_e32 v87, 0x80000000, v212
	v_xor_b32_e32 v88, 0x80000000, v212
	v_xor_b32_e32 v89, 0x80000000, v212
	v_xor_b32_e32 v90, 0x80000000, v212
	v_xor_b32_e32 v91, 0x80000000, v212
	v_xor_b32_e32 v92, 0x80000000, v212
	v_xor_b32_e32 v93, 0x80000000, v212
	v_xor_b32_e32 v94, 0x80000000, v212
	v_xor_b32_e32 v95, 0x80000000, v212
	v_xor_b32_e32 v96, 0x80000000, v212
	v_xor_b32_e32 v97, 0x80000000, v212
	v_xor_b32_e32 v98, 0x80000000, v212
	v_xor_b32_e32 v99, 0x80000000, v212
	v_exp_f32_e64 v215, -v214
	v_mov_b32_e32 v220, 1
	s_mov_b32 s54, 1
	v_mul_f32_e32 v213, v213, v215
	v_add_u32_e32 v221, s44, v235
	v_add_u32_e32 v221, v221, v240
	ds_write_b32 v221, v215
; #define WAIT_BAR(N) asm volatile("s_waitcnt vmcnt(" #N ") lgkmcnt(0)\n\ts_barrier":::"memory")
;   #define DMA_K(t,slot) glds16(ksrc+(long)(t)*KVBLK*KP,(unsigned)__builtin_amdgcn_readfirstlane(kdst+(slot)))
;   #define DMA_V(t,slot) glds16(vsrc+(long)(t)*KVBLK*KP,(unsigned)__builtin_amdgcn_readfirstlane(vdst+(slot)))
;   #define CMASK(P0,P1,t) do{int jb_=(t)-(NT-4); if(jb_>=0)cmask(P0,P1,jb_,vlim);}while(0)
;   #define START(P0,P1) do{ const float rm=rowmax(P0,P1); resc=false; \
;     { const float dl=rm; mhat=fadd_s(mhat,dl); \
;       _Pragma("unroll") for(int r=0;r<16;++r){P0[r]=fsub_s(P0[r],dl);P1[r]=fsub_s(P1[r],dl);} \
;       _Pragma("unroll") for(int r=0;r<16;++r)negm[r]=-mhat; asm volatile("":"+v"(negm)); } \
;     _Pragma("unroll") for(int r=0;r<16;++r)P0[r]=__builtin_amdgcn_exp2f(P0[r]); }while(0)
;   #define ROT() do{sl_prev=sl_cur;sl_cur=sl_next;sl_next=(sl_next==(NSLOT-1)*SLOTB)?0:sl_next+SLOTB;}while(0)
;   #define CMASK(P0,P1,t) do{}while(0)
;   #define CMASK(P0,P1,t) do{int jb_=(t)-(NT-4); if(jb_>=0)cmask(P0,P1,jb_,vlim);}while(0)
; template<int THRL,bool PART> __device__ __forceinline__ int attn_unit(const bf16*Qb,const bf16*__restrict__ Kh,const bf16*__restrict__ Vh,bf16*Ob,const int NT,const int vlim_in,char*shm,const int s0,const bool primed,const bf16*nKh,const bf16*nVh,bf16*fuseM,const float lam){
;     ...
;   if(act){
;   qkt(pA0,pA1,Kbase,qr,negm,r32,hi);asm volatile("s_nop 15\n\ts_nop 7":"+v"(pA0),"+v"(pA1));CMASK(pA0,pA1,0);
;   START(pA0,pA1);
;   _Pragma("unroll") for(int r=0;r<16;++r)pA1[r]=__builtin_amdgcn_exp2f(pA1[r]);
;   }
;   WAIT_BAR(0);
;   DMA_K(3,s0);DMA_V(1,s1);
;   ROT();
;   if(act)kload8(kf,kp0+sl_cur);
.Lat_nores14:
	v_add_u32_e32 v221, s46, v235
	ds_write_b32 v221, v220 offset:256
	v_add_u32_e32 v216, s26, v232
	s_waitcnt lgkmcnt(2)
	v_mfma_f32_32x32x16_bf16 v[148:163], v[100:103], v[116:119], v[148:163]
	v_exp_f32_e32 v52, v52
	v_exp_f32_e32 v53, v53
	v_exp_f32_e32 v54, v54
	v_exp_f32_e32 v55, v55
	v_mfma_f32_32x32x16_bf16 v[164:179], v[100:103], v[132:135], v[164:179]
	v_exp_f32_e32 v56, v56
	v_exp_f32_e32 v57, v57
	v_exp_f32_e32 v58, v58
	v_exp_f32_e32 v59, v59
	s_add_i32 s34, s17, 1
	s_cmp_lt_u32 s34, s16
	s_cbranch_scc0 .Lat_nokf15
	v_mfma_f32_32x32x16_bf16 v[148:163], v[104:107], v[120:123], v[148:163]
	v_exp_f32_e32 v60, v60
	v_exp_f32_e32 v61, v61
	v_exp_f32_e32 v62, v62
	v_exp_f32_e32 v63, v63
	ds_read_b128 v[20:23], v216 offset:0
	ds_read_b128 v[24:27], v216 offset:512
	v_mfma_f32_32x32x16_bf16 v[164:179], v[104:107], v[136:139], v[164:179]
	v_exp_f32_e32 v64, v64
	v_exp_f32_e32 v65, v65
	v_exp_f32_e32 v66, v66
	v_exp_f32_e32 v67, v67
	ds_read_b128 v[28:31], v216 offset:2048
	ds_read_b128 v[32:35], v216 offset:2560
	v_mfma_f32_32x32x16_bf16 v[148:163], v[108:111], v[124:127], v[148:163]
	v_exp_f32_e32 v68, v68
	v_exp_f32_e32 v69, v69
	v_exp_f32_e32 v70, v70
	v_exp_f32_e32 v71, v71
	ds_read_b128 v[36:39], v216 offset:4096
	ds_read_b128 v[40:43], v216 offset:4608
	v_mfma_f32_32x32x16_bf16 v[164:179], v[108:111], v[140:143], v[164:179]
	v_exp_f32_e32 v72, v72
	v_exp_f32_e32 v73, v73
	v_exp_f32_e32 v74, v74
	v_exp_f32_e32 v75, v75
	ds_read_b128 v[44:47], v216 offset:6144
	ds_read_b128 v[48:51], v216 offset:6656
	v_mfma_f32_32x32x16_bf16 v[148:163], v[112:115], v[128:131], v[148:163]
	v_exp_f32_e32 v76, v76
	v_exp_f32_e32 v77, v77
	v_exp_f32_e32 v78, v78
	v_exp_f32_e32 v79, v79
	v_mfma_f32_32x32x16_bf16 v[164:179], v[112:115], v[144:147], v[164:179]
	v_exp_f32_e32 v80, v80
	v_exp_f32_e32 v81, v81
	v_exp_f32_e32 v82, v82
	v_exp_f32_e32 v83, v83
	s_branch .Lat_Aend13
.Lat_nokf15:
	v_mfma_f32_32x32x16_bf16 v[148:163], v[104:107], v[120:123], v[148:163]
	v_exp_f32_e32 v60, v60
	v_exp_f32_e32 v61, v61
	v_exp_f32_e32 v62, v62
	v_exp_f32_e32 v63, v63
	v_mfma_f32_32x32x16_bf16 v[164:179], v[104:107], v[136:139], v[164:179]
	v_exp_f32_e32 v64, v64
	v_exp_f32_e32 v65, v65
	v_exp_f32_e32 v66, v66
	v_exp_f32_e32 v67, v67
	v_mfma_f32_32x32x16_bf16 v[148:163], v[108:111], v[124:127], v[148:163]
	v_exp_f32_e32 v68, v68
	v_exp_f32_e32 v69, v69
	v_exp_f32_e32 v70, v70
	v_exp_f32_e32 v71, v71
	v_mfma_f32_32x32x16_bf16 v[164:179], v[108:111], v[140:143], v[164:179]
	v_exp_f32_e32 v72, v72
	v_exp_f32_e32 v73, v73
	v_exp_f32_e32 v74, v74
	v_exp_f32_e32 v75, v75
	v_mfma_f32_32x32x16_bf16 v[148:163], v[112:115], v[128:131], v[148:163]
	v_exp_f32_e32 v76, v76
	v_exp_f32_e32 v77, v77
	v_exp_f32_e32 v78, v78
	v_exp_f32_e32 v79, v79
	v_mfma_f32_32x32x16_bf16 v[164:179], v[112:115], v[144:147], v[164:179]
	v_exp_f32_e32 v80, v80
	v_exp_f32_e32 v81, v81
	v_exp_f32_e32 v82, v82
	v_exp_f32_e32 v83, v83
	s_branch .Lat_Aend13
.Lat_Afirst10:
	s_waitcnt lgkmcnt(0)
	v_mfma_f32_32x32x16_bf16 v[52:67], v[20:23], v[4:7], v[84:99]
	v_mfma_f32_32x32x16_bf16 v[68:83], v[24:27], v[4:7], v[84:99]
	v_mfma_f32_32x32x16_bf16 v[52:67], v[28:31], v[8:11], v[52:67]
	v_mfma_f32_32x32x16_bf16 v[68:83], v[32:35], v[8:11], v[68:83]
	v_mfma_f32_32x32x16_bf16 v[52:67], v[36:39], v[12:15], v[52:67]
	v_mfma_f32_32x32x16_bf16 v[68:83], v[40:43], v[12:15], v[68:83]
	v_mfma_f32_32x32x16_bf16 v[52:67], v[44:47], v[16:19], v[52:67]
	v_mfma_f32_32x32x16_bf16 v[68:83], v[48:51], v[16:19], v[68:83]
	s_nop 7
	s_nop 4
	v_max3_f32 v218, v52, v53, v54
	v_max3_f32 v219, v55, v56, v57
	v_max3_f32 v218, v218, v58, v59
	v_max3_f32 v219, v219, v60, v61
	v_max3_f32 v218, v218, v62, v63
	v_max3_f32 v219, v219, v64, v65
	v_max3_f32 v218, v218, v66, v67
	v_max3_f32 v219, v219, v68, v69
	v_max3_f32 v218, v218, v70, v71
	v_max3_f32 v219, v219, v72, v73
	v_max3_f32 v218, v218, v74, v75
	v_max3_f32 v219, v219, v76, v77
	v_max3_f32 v218, v218, v78, v79
	v_max3_f32 v219, v219, v80, v81
	v_max3_f32 v218, v218, v82, v83
	v_max_f32_e32 v214, v218, v219
	v_mov_b32_e32 v218, v214
	s_nop 1
	v_permlane32_swap_b32_e32 v214, v218
	v_max_f32_e32 v214, v214, v218
	s_mov_b32 s54, 0
	v_mov_b32_e32 v220, 0
	v_mov_b32_e32 v212, v214
	v_sub_f32_e32 v52, v52, v214
	v_sub_f32_e32 v53, v53, v214
	v_sub_f32_e32 v54, v54, v214
	v_sub_f32_e32 v55, v55, v214
	v_sub_f32_e32 v56, v56, v214
	v_sub_f32_e32 v57, v57, v214
	v_sub_f32_e32 v58, v58, v214
	v_sub_f32_e32 v59, v59, v214
	v_sub_f32_e32 v60, v60, v214
	v_sub_f32_e32 v61, v61, v214
	v_sub_f32_e32 v62, v62, v214
	v_sub_f32_e32 v63, v63, v214
	v_sub_f32_e32 v64, v64, v214
	v_sub_f32_e32 v65, v65, v214
	v_sub_f32_e32 v66, v66, v214
	v_sub_f32_e32 v67, v67, v214
	v_sub_f32_e32 v68, v68, v214
	v_sub_f32_e32 v69, v69, v214
	v_sub_f32_e32 v70, v70, v214
	v_sub_f32_e32 v71, v71, v214
	v_sub_f32_e32 v72, v72, v214
	v_sub_f32_e32 v73, v73, v214
	v_sub_f32_e32 v74, v74, v214
	v_sub_f32_e32 v75, v75, v214
	v_sub_f32_e32 v76, v76, v214
	v_sub_f32_e32 v77, v77, v214
	v_sub_f32_e32 v78, v78, v214
	v_sub_f32_e32 v79, v79, v214
	v_sub_f32_e32 v80, v80, v214
	v_sub_f32_e32 v81, v81, v214
	v_sub_f32_e32 v82, v82, v214
	v_sub_f32_e32 v83, v83, v214
	v_xor_b32_e32 v84, 0x80000000, v212
	v_xor_b32_e32 v85, 0x80000000, v212
	v_xor_b32_e32 v86, 0x80000000, v212
	v_xor_b32_e32 v87, 0x80000000, v212
	v_xor_b32_e32 v88, 0x80000000, v212
	v_xor_b32_e32 v89, 0x80000000, v212
	v_xor_b32_e32 v90, 0x80000000, v212
	v_xor_b32_e32 v91, 0x80000000, v212
	v_xor_b32_e32 v92, 0x80000000, v212
	v_xor_b32_e32 v93, 0x80000000, v212
	v_xor_b32_e32 v94, 0x80000000, v212
	v_xor_b32_e32 v95, 0x80000000, v212
	v_xor_b32_e32 v96, 0x80000000, v212
	v_xor_b32_e32 v97, 0x80000000, v212
	v_xor_b32_e32 v98, 0x80000000, v212
	v_xor_b32_e32 v99, 0x80000000, v212
	v_add_u32_e32 v221, s46, v235
	ds_write_b32 v221, v220 offset:256
	s_cmp_gt_u32 s16, 1
	s_cbranch_scc0 .Lat_nokf16
	v_add_u32_e32 v216, s26, v232
	ds_read_b128 v[20:23], v216 offset:0
	ds_read_b128 v[24:27], v216 offset:512
	ds_read_b128 v[28:31], v216 offset:2048
	ds_read_b128 v[32:35], v216 offset:2560
	ds_read_b128 v[36:39], v216 offset:4096
	ds_read_b128 v[40:43], v216 offset:4608
	ds_read_b128 v[44:47], v216 offset:6144
	ds_read_b128 v[48:51], v216 offset:6656
; #define SBAR() __builtin_amdgcn_sched_barrier(0)
;   #define RESC() do{ if(resc){ asm volatile("s_waitcnt lgkmcnt(0)":::"memory"); \
;       _Pragma("unroll") for(int d_=0;d_<2;++d_) _Pragma("unroll") for(int r=0;r<16;++r)o[d_][r]*=wsf[crow(r,hi)]; } }while(0)
;   #define PKW(P,B) cvtpk_s(P[B],P[B+1])
; template<int THRL,bool PART> __device__ __forceinline__ int attn_unit(const bf16*Qb,const bf16*__restrict__ Kh,const bf16*__restrict__ Vh,bf16*Ob,const int NT,const int vlim_in,char*shm,const int s0,const bool primed,const bf16*nKh,const bf16*nVh,bf16*fuseM,const float lam){
;     ...
;   STEP(pB0,pB1,pA0,pA1,NT-1,false,false,false); RESC();
;   if(act){ float sacc=pB0[0]+pB0[1]; _Pragma("unroll") for(int r=2;r<16;++r)sacc+=pB0[r]; _Pragma("unroll") for(int r=0;r<16;++r)sacc+=pB1[r]; l_reg+=sacc;
;     pw0=(u32x4){PKW(pB0,0),PKW(pB0,2),PKW(pB0,4),PKW(pB0,6)};pw1=(u32x4){PKW(pB0,8),PKW(pB0,10),PKW(pB0,12),PKW(pB0,14)};pw2=(u32x4){PKW(pB1,0),PKW(pB1,2),PKW(pB1,4),PKW(pB1,6)};pw3=(u32x4){PKW(pB1,8),PKW(pB1,10),PKW(pB1,12),PKW(pB1,14)};
;     SBAR(); pv(o,vb0+sl_cur,PAF(0),PAF(1),PAF(2),PAF(3)); }
.Lat_nokf16:
	v_exp_f32_e32 v52, v52
	v_exp_f32_e32 v53, v53
	v_exp_f32_e32 v54, v54
	v_exp_f32_e32 v55, v55
	v_exp_f32_e32 v56, v56
	v_exp_f32_e32 v57, v57
	v_exp_f32_e32 v58, v58
	v_exp_f32_e32 v59, v59
	v_exp_f32_e32 v60, v60
	v_exp_f32_e32 v61, v61
	v_exp_f32_e32 v62, v62
	v_exp_f32_e32 v63, v63
	v_exp_f32_e32 v64, v64
	v_exp_f32_e32 v65, v65
	v_exp_f32_e32 v66, v66
	v_exp_f32_e32 v67, v67
	v_exp_f32_e32 v68, v68
	v_exp_f32_e32 v69, v69
	v_exp_f32_e32 v70, v70
	v_exp_f32_e32 v71, v71
	v_exp_f32_e32 v72, v72
	v_exp_f32_e32 v73, v73
	v_exp_f32_e32 v74, v74
	v_exp_f32_e32 v75, v75
	v_exp_f32_e32 v76, v76
	v_exp_f32_e32 v77, v77
	v_exp_f32_e32 v78, v78
	v_exp_f32_e32 v79, v79
	v_exp_f32_e32 v80, v80
	v_exp_f32_e32 v81, v81
	v_exp_f32_e32 v82, v82
	v_exp_f32_e32 v83, v83
	s_branch .Lat_Aend13
.Lat_Alast12:
	s_mov_b32 s54, 0
	s_cmp_eq_u32 s17, s16
	s_cbranch_scc0 .Lat_Aend13
	v_add_u32_e32 v217, s28, v233
	v_add_u32_e32 v222, s31, v234
	ds_read_b64_tr_b16 v[116:117], v217 offset:0
	ds_read_b64_tr_b16 v[118:119], v217 offset:512
	v_add_f32_e32 v243, v180, v181
	v_add_f32_e32 v243, v243, v182
	v_add_f32_e32 v243, v243, v183
	v_add_f32_e32 v243, v243, v184
	v_add_f32_e32 v243, v243, v185
	v_cvt_pk_bf16_f32 v100, v180, v181
	v_cvt_pk_bf16_f32 v101, v182, v183
	ds_read_b64_tr_b16 v[132:133], v217 offset:4096
	ds_read_b64_tr_b16 v[134:135], v217 offset:4608
	v_add_f32_e32 v243, v243, v186
	v_add_f32_e32 v243, v243, v187
	v_add_f32_e32 v243, v243, v188
	v_add_f32_e32 v243, v243, v189
	v_cvt_pk_bf16_f32 v102, v184, v185
	v_cvt_pk_bf16_f32 v103, v186, v187
	ds_write_b128 v222, v[100:103] offset:0
	ds_read_b64_tr_b16 v[120:121], v217 offset:1024
	ds_read_b64_tr_b16 v[122:123], v217 offset:1536
	v_add_f32_e32 v243, v243, v190
	v_add_f32_e32 v243, v243, v191
	v_add_f32_e32 v243, v243, v192
	v_add_f32_e32 v243, v243, v193
	v_cvt_pk_bf16_f32 v104, v188, v189
	v_cvt_pk_bf16_f32 v105, v190, v191
	ds_read_b64_tr_b16 v[136:137], v217 offset:5120
	ds_read_b64_tr_b16 v[138:139], v217 offset:5632
	v_add_f32_e32 v243, v243, v194
	v_add_f32_e32 v243, v243, v195
	v_add_f32_e32 v243, v243, v196
	v_add_f32_e32 v243, v243, v197
	v_cvt_pk_bf16_f32 v106, v192, v193
	v_cvt_pk_bf16_f32 v107, v194, v195
	ds_write_b128 v222, v[104:107] offset:1024
	ds_read_b64_tr_b16 v[124:125], v217 offset:2048
	ds_read_b64_tr_b16 v[126:127], v217 offset:2560
	v_add_f32_e32 v243, v243, v198
	v_add_f32_e32 v243, v243, v199
	v_add_f32_e32 v243, v243, v200
	v_add_f32_e32 v243, v243, v201
	v_cvt_pk_bf16_f32 v108, v196, v197
	v_cvt_pk_bf16_f32 v109, v198, v199
	ds_read_b64_tr_b16 v[140:141], v217 offset:6144
	ds_read_b64_tr_b16 v[142:143], v217 offset:6656
	v_add_f32_e32 v243, v243, v202
	v_add_f32_e32 v243, v243, v203
	v_add_f32_e32 v243, v243, v204
	v_add_f32_e32 v243, v243, v205
	v_cvt_pk_bf16_f32 v110, v200, v201
	v_cvt_pk_bf16_f32 v111, v202, v203
	ds_write_b128 v222, v[108:111] offset:2048
	ds_read_b64_tr_b16 v[128:129], v217 offset:3072
	ds_read_b64_tr_b16 v[130:131], v217 offset:3584
	v_add_f32_e32 v243, v243, v206
	v_add_f32_e32 v243, v243, v207
	v_add_f32_e32 v243, v243, v208
	v_add_f32_e32 v243, v243, v209
	v_cvt_pk_bf16_f32 v112, v204, v205
	v_cvt_pk_bf16_f32 v113, v206, v207
	ds_read_b64_tr_b16 v[144:145], v217 offset:7168
	ds_read_b64_tr_b16 v[146:147], v217 offset:7680
	v_add_f32_e32 v243, v243, v210
	v_add_f32_e32 v243, v243, v211
	v_cvt_pk_bf16_f32 v114, v208, v209
	v_cvt_pk_bf16_f32 v115, v210, v211
	ds_write_b128 v222, v[112:115] offset:3072
	v_add_f32_e32 v213, v213, v243
	v_mov_b32_e32 v220, 0
	v_add_u32_e32 v221, s46, v235
	ds_write_b32 v221, v220 offset:256
	s_waitcnt lgkmcnt(2)
	v_mfma_f32_32x32x16_bf16 v[148:163], v[100:103], v[116:119], v[148:163]
	v_mfma_f32_32x32x16_bf16 v[164:179], v[100:103], v[132:135], v[164:179]
	v_mfma_f32_32x32x16_bf16 v[148:163], v[104:107], v[120:123], v[148:163]
	v_mfma_f32_32x32x16_bf16 v[164:179], v[104:107], v[136:139], v[164:179]
	v_mfma_f32_32x32x16_bf16 v[148:163], v[108:111], v[124:127], v[148:163]
	v_mfma_f32_32x32x16_bf16 v[164:179], v[108:111], v[140:143], v[164:179]
	v_mfma_f32_32x32x16_bf16 v[148:163], v[112:115], v[128:131], v[148:163]
	v_mfma_f32_32x32x16_bf16 v[164:179], v[112:115], v[144:147], v[164:179]
.Lat_Aend13:
	s_cmp_eq_u32 s54, 0
	s_cbranch_scc1 .Lat_nor17
	v_add_u32_e32 v221, s44, v235
	v_add_u32_e32 v221, v221, v241
	ds_read_b128 v[116:119], v221 offset:0
	ds_read_b128 v[120:123], v221 offset:32
	ds_read_b128 v[124:127], v221 offset:64
	ds_read_b128 v[128:131], v221 offset:96
	s_nop 7
	s_nop 3
	s_waitcnt lgkmcnt(0)
	v_mul_f32_e32 v148, v148, v116
	v_mul_f32_e32 v149, v149, v117
	v_mul_f32_e32 v150, v150, v118
	v_mul_f32_e32 v151, v151, v119
	v_mul_f32_e32 v152, v152, v120
	v_mul_f32_e32 v153, v153, v121
	v_mul_f32_e32 v154, v154, v122
	v_mul_f32_e32 v155, v155, v123
	v_mul_f32_e32 v156, v156, v124
	v_mul_f32_e32 v157, v157, v125
	v_mul_f32_e32 v158, v158, v126
	v_mul_f32_e32 v159, v159, v127
	v_mul_f32_e32 v160, v160, v128
	v_mul_f32_e32 v161, v161, v129
	v_mul_f32_e32 v162, v162, v130
	v_mul_f32_e32 v163, v163, v131
	v_mul_f32_e32 v164, v164, v116
	v_mul_f32_e32 v165, v165, v117
	v_mul_f32_e32 v166, v166, v118
	v_mul_f32_e32 v167, v167, v119
	v_mul_f32_e32 v168, v168, v120
	v_mul_f32_e32 v169, v169, v121
	v_mul_f32_e32 v170, v170, v122
	v_mul_f32_e32 v171, v171, v123
	v_mul_f32_e32 v172, v172, v124
	v_mul_f32_e32 v173, v173, v125
	v_mul_f32_e32 v174, v174, v126
	v_mul_f32_e32 v175, v175, v127
	v_mul_f32_e32 v176, v176, v128
	v_mul_f32_e32 v177, v177, v129
	v_mul_f32_e32 v178, v178, v130
	v_mul_f32_e32 v179, v179, v131
; #define SBAR() __builtin_amdgcn_sched_barrier(0)
; __device__ __forceinline__ void pv(f32x16*o,int vb,bf16x8 pa0,bf16x8 pa1,bf16x8 pa2,bf16x8 pa3){
;   #pragma unroll
;   for(int d0=0;d0<2;++d0){s16x4 lo[4],hi[4];
;     #pragma unroll
;     for(int ks=0;ks<4;++ks){
;       asm volatile("ds_read_b64_tr_b16 %0,%1 offset:%c2":"=&v"(lo[ks]):"v"(vb),"i"(d0*4096+ks*1024):"memory");
;       asm volatile("ds_read_b64_tr_b16 %0,%1 offset:%c2":"=&v"(hi[ks]):"v"(vb),"i"(d0*4096+ks*1024+512):"memory");}
;     asm volatile("s_waitcnt lgkmcnt(0)":::"memory");SBAR();
;     ...
;     o[d0]=__builtin_amdgcn_mfma_f32_32x32x16_bf16(pa0,PK(0),o[d0],0,0,0);
;     o[d0]=__builtin_amdgcn_mfma_f32_32x32x16_bf16(pa1,PK(1),o[d0],0,0,0);
;     o[d0]=__builtin_amdgcn_mfma_f32_32x32x16_bf16(pa2,PK(2),o[d0],0,0,0);
;     o[d0]=__builtin_amdgcn_mfma_f32_32x32x16_bf16(pa3,PK(3),o[d0],0,0,0);
;     ...
;   }
; }
.Lat_nor17:
	s_waitcnt lgkmcnt(0)
	s_branch .Lat_bar9
.Lat_B7:
	s_cmp_lt_u32 s17, 2
	s_cbranch_scc1 .Lat_Bend18
	s_add_i32 s34, s16, 1
	s_cmp_le_u32 s17, s34
	s_cbranch_scc0 .Lat_Bend18
	v_add_u32_e32 v221, s32, v234
	ds_read_b128 v[100:103], v221 offset:0
	ds_read_b128 v[104:107], v221 offset:1024
	ds_read_b128 v[108:111], v221 offset:2048
	ds_read_b128 v[112:115], v221 offset:3072
	v_add_u32_e32 v217, s29, v233
	ds_read_b64_tr_b16 v[116:117], v217 offset:0
	ds_read_b64_tr_b16 v[118:119], v217 offset:512
	ds_read_b64_tr_b16 v[132:133], v217 offset:4096
	ds_read_b64_tr_b16 v[134:135], v217 offset:4608
	ds_read_b64_tr_b16 v[120:121], v217 offset:1024
	ds_read_b64_tr_b16 v[122:123], v217 offset:1536
	ds_read_b64_tr_b16 v[136:137], v217 offset:5120
	ds_read_b64_tr_b16 v[138:139], v217 offset:5632
	ds_read_b64_tr_b16 v[124:125], v217 offset:2048
	ds_read_b64_tr_b16 v[126:127], v217 offset:2560
	ds_read_b64_tr_b16 v[140:141], v217 offset:6144
	ds_read_b64_tr_b16 v[142:143], v217 offset:6656
	ds_read_b64_tr_b16 v[128:129], v217 offset:3072
	ds_read_b64_tr_b16 v[130:131], v217 offset:3584
	ds_read_b64_tr_b16 v[144:145], v217 offset:7168
	ds_read_b64_tr_b16 v[146:147], v217 offset:7680
	v_add_u32_e32 v221, s47, v235
	ds_read_b32 v220, v221 offset:256
	s_waitcnt lgkmcnt(13)
	v_mfma_f32_32x32x16_bf16 v[148:163], v[100:103], v[116:119], v[148:163]
	v_mfma_f32_32x32x16_bf16 v[164:179], v[100:103], v[132:135], v[164:179]
	s_waitcnt lgkmcnt(9)
	v_mfma_f32_32x32x16_bf16 v[148:163], v[104:107], v[120:123], v[148:163]
	v_mfma_f32_32x32x16_bf16 v[164:179], v[104:107], v[136:139], v[164:179]
	s_waitcnt lgkmcnt(5)
	v_mfma_f32_32x32x16_bf16 v[148:163], v[108:111], v[124:127], v[148:163]
	v_mfma_f32_32x32x16_bf16 v[164:179], v[108:111], v[140:143], v[164:179]
	s_waitcnt lgkmcnt(1)
	v_mfma_f32_32x32x16_bf16 v[148:163], v[112:115], v[128:131], v[148:163]
	v_mfma_f32_32x32x16_bf16 v[164:179], v[112:115], v[144:147], v[164:179]
	s_waitcnt lgkmcnt(0)
	v_readfirstlane_b32 s42, v220
	s_cmp_eq_u32 s42, 0
	s_cbranch_scc1 .Lat_Bnores19
	v_add_u32_e32 v221, s45, v235
	v_add_u32_e32 v221, v221, v241
	ds_read_b128 v[116:119], v221 offset:0
	ds_read_b128 v[120:123], v221 offset:32
	ds_read_b128 v[124:127], v221 offset:64
	ds_read_b128 v[128:131], v221 offset:96
	s_nop 7
	s_nop 3
	s_waitcnt lgkmcnt(0)
	v_mul_f32_e32 v148, v148, v116
	v_mul_f32_e32 v149, v149, v117
	v_mul_f32_e32 v150, v150, v118
	v_mul_f32_e32 v151, v151, v119
	v_mul_f32_e32 v152, v152, v120
	v_mul_f32_e32 v153, v153, v121
	v_mul_f32_e32 v154, v154, v122
	v_mul_f32_e32 v155, v155, v123
	v_mul_f32_e32 v156, v156, v124
	v_mul_f32_e32 v157, v157, v125
	v_mul_f32_e32 v158, v158, v126
	v_mul_f32_e32 v159, v159, v127
	v_mul_f32_e32 v160, v160, v128
	v_mul_f32_e32 v161, v161, v129
	v_mul_f32_e32 v162, v162, v130
	v_mul_f32_e32 v163, v163, v131
	v_mul_f32_e32 v164, v164, v116
	v_mul_f32_e32 v165, v165, v117
	v_mul_f32_e32 v166, v166, v118
	v_mul_f32_e32 v167, v167, v119
	v_mul_f32_e32 v168, v168, v120
	v_mul_f32_e32 v169, v169, v121
	v_mul_f32_e32 v170, v170, v122
	v_mul_f32_e32 v171, v171, v123
	v_mul_f32_e32 v172, v172, v124
	v_mul_f32_e32 v173, v173, v125
	v_mul_f32_e32 v174, v174, v126
	v_mul_f32_e32 v175, v175, v127
	v_mul_f32_e32 v176, v176, v128
	v_mul_f32_e32 v177, v177, v129
	v_mul_f32_e32 v178, v178, v130
	v_mul_f32_e32 v179, v179, v131
.Lat_Bnores19:
.Lat_Bend18:
	s_add_i32 s34, s17, 1
	s_cmp_lt_u32 s34, s15
	s_cbranch_scc0 .Lat_dn21
	s_lshl_b32 s37, s5, 10
	s_add_i32 m0, s37, s30
	s_mov_b64 s[38:39], s[20:21]
	global_load_lds_dwordx4 v237, s[38:39]
	s_add_i32 m0, m0, 0x1000
	s_add_u32 s38, s38, 64
	s_addc_u32 s39, s39, 0
	global_load_lds_dwordx4 v237, s[38:39]
	s_add_i32 m0, m0, 0x1000
	s_add_u32 s38, s38, 64
	s_addc_u32 s39, s39, 0
	global_load_lds_dwordx4 v237, s[38:39]
	s_add_i32 m0, m0, 0x1000
	s_add_u32 s38, s38, 64
	s_addc_u32 s39, s39, 0
	global_load_lds_dwordx4 v237, s[38:39]
	s_add_u32 s20, s20, 0x10000
	s_addc_u32 s21, s21, 0
	s_add_i32 s34, s17, 3
	s_cmp_lt_u32 s34, s15
	s_cbranch_scc0 .Lat_dv20
	s_lshl_b32 s37, s5, 10
	s_add_i32 m0, s37, s27
	s_add_u32 s38, s18, 64
	s_addc_u32 s39, s19, 0
	global_load_lds_dwordx4 v236, s[18:19]
	s_add_i32 m0, m0, 0x1000
	s_nop 0
	global_load_lds_dwordx4 v236, s[38:39]
	s_add_u32 s18, s18, 0x10000
	s_addc_u32 s19, s19, 0
	s_waitcnt vmcnt(6) lgkmcnt(0)
	s_branch .Lat_bar9
.Lat_dv20:
	s_waitcnt vmcnt(4) lgkmcnt(0)
	s_branch .Lat_bar9

; #define WAIT_BAR(N) asm volatile("s_waitcnt vmcnt(" #N ") lgkmcnt(0)\n\ts_barrier":::"memory")
;   #define RESC() do{ if(resc){ asm volatile("s_waitcnt lgkmcnt(0)":::"memory"); \
;       _Pragma("unroll") for(int d_=0;d_<2;++d_) _Pragma("unroll") for(int r=0;r<16;++r)o[d_][r]*=wsf[crow(r,hi)]; } }while(0)
;   #define ROT() do{sl_prev=sl_cur;sl_cur=sl_next;sl_next=(sl_next==(NSLOT-1)*SLOTB)?0:sl_next+SLOTB;}while(0)
; template<int THRL,bool PART> __device__ __forceinline__ int attn_unit(const bf16*Qb,const bf16*__restrict__ Kh,const bf16*__restrict__ Vh,bf16*Ob,const int NT,const int vlim_in,char*shm,const int s0,const bool primed,const bf16*nKh,const bf16*nVh,bf16*fuseM,const float lam){
;     ...
;   for(;t+5<NT;t+=2){
;     STEP(pB0,pB1,pA0,pA1,t,true,true,true);     WAIT_BAR(2); RESC(); ROT();
;     STEP(pA0,pA1,pB0,pB1,t+1,true,true,true);   WAIT_BAR(2); RESC(); ROT();
;   }
.Lat_bar9:
	s_barrier
	s_add_i32 s24, s24, 1
	s_cmp_eq_u32 s24, 3
	s_cselect_b32 s24, 0, s24
	s_add_i32 s25, s25, 1
	s_and_b32 s25, s25, 3
	s_add_i32 s17, s17, 1
	s_add_i32 s34, s15, 1
	s_cmp_le_u32 s17, s34
	s_cbranch_scc0 .Lat_tx6
	s_add_i32 s26, s24, 1
	s_cmp_ge_u32 s26, 3
	s_cselect_b32 s35, 3, 0
	s_sub_i32 s26, s26, s35
	s_lshl_b32 s26, s26, 13
	s_lshl_b32 s27, s24, 13
	s_add_i32 s28, s25, 3
	s_and_b32 s28, s28, 3
	s_lshl_b32 s28, s28, 14
	s_add_i32 s28, s28, 0x6000
	s_add_i32 s29, s25, 2
	s_and_b32 s29, s29, 3
	s_lshl_b32 s29, s29, 14
	s_add_i32 s29, s29, 0x6000
	s_add_i32 s30, s25, 1
	s_and_b32 s30, s30, 3
	s_lshl_b32 s30, s30, 14
	s_add_i32 s30, s30, 0x6000
	s_and_b32 s34, s17, 1
	s_lshl_b32 s32, s34, 14
	s_xor_b32 s31, s32, 0x4000
	s_lshl_b32 s44, s34, 7
	s_xor_b32 s45, s44, 0x80
	s_lshl_b32 s46, s34, 2
	s_xor_b32 s47, s46, 4
	s_cmp_lg_u32 s6, 0
	s_cbranch_scc1 .Lat_B22
	s_cmp_lt_u32 s17, s16
	s_cbranch_scc0 .Lat_Alast27
.Lat_Asteady26:
	v_add_u32_e32 v217, s28, v233
	v_add_u32_e32 v222, s31, v234
	s_waitcnt lgkmcnt(0)
	ds_read_b64_tr_b16 v[116:117], v217 offset:0
	ds_read_b64_tr_b16 v[118:119], v217 offset:512
	v_mfma_f32_32x32x16_bf16 v[180:195], v[20:23], v[4:7], v[84:99]
	v_add_f32_e32 v243, v52, v53
	v_add_f32_e32 v243, v243, v54
	v_add_f32_e32 v243, v243, v55
	v_add_f32_e32 v243, v243, v56
	v_add_f32_e32 v243, v243, v57
	v_cvt_pk_bf16_f32 v100, v52, v53
	v_cvt_pk_bf16_f32 v101, v54, v55
	ds_read_b64_tr_b16 v[132:133], v217 offset:4096
	ds_read_b64_tr_b16 v[134:135], v217 offset:4608
	v_mfma_f32_32x32x16_bf16 v[196:211], v[24:27], v[4:7], v[84:99]
	v_add_f32_e32 v243, v243, v58
	v_add_f32_e32 v243, v243, v59
	v_add_f32_e32 v243, v243, v60
	v_add_f32_e32 v243, v243, v61
	v_cvt_pk_bf16_f32 v102, v56, v57
	v_cvt_pk_bf16_f32 v103, v58, v59
	ds_write_b128 v222, v[100:103] offset:0
	ds_read_b64_tr_b16 v[120:121], v217 offset:1024
	ds_read_b64_tr_b16 v[122:123], v217 offset:1536
	v_mfma_f32_32x32x16_bf16 v[180:195], v[28:31], v[8:11], v[180:195]
	v_add_f32_e32 v243, v243, v62
	v_add_f32_e32 v243, v243, v63
	v_add_f32_e32 v243, v243, v64
	v_add_f32_e32 v243, v243, v65
	v_cvt_pk_bf16_f32 v104, v60, v61
	v_cvt_pk_bf16_f32 v105, v62, v63
	ds_read_b64_tr_b16 v[136:137], v217 offset:5120
	ds_read_b64_tr_b16 v[138:139], v217 offset:5632
	v_mfma_f32_32x32x16_bf16 v[196:211], v[32:35], v[8:11], v[196:211]
	v_add_f32_e32 v243, v243, v66
	v_add_f32_e32 v243, v243, v67
	v_add_f32_e32 v243, v243, v68
	v_add_f32_e32 v243, v243, v69
	v_cvt_pk_bf16_f32 v106, v64, v65
	v_cvt_pk_bf16_f32 v107, v66, v67
	ds_write_b128 v222, v[104:107] offset:1024
	ds_read_b64_tr_b16 v[124:125], v217 offset:2048
	ds_read_b64_tr_b16 v[126:127], v217 offset:2560
	v_mfma_f32_32x32x16_bf16 v[180:195], v[36:39], v[12:15], v[180:195]
	v_add_f32_e32 v243, v243, v70
	v_add_f32_e32 v243, v243, v71
	v_add_f32_e32 v243, v243, v72
	v_add_f32_e32 v243, v243, v73
	v_cvt_pk_bf16_f32 v108, v68, v69
	v_cvt_pk_bf16_f32 v109, v70, v71
	ds_read_b64_tr_b16 v[140:141], v217 offset:6144
	ds_read_b64_tr_b16 v[142:143], v217 offset:6656
	v_mfma_f32_32x32x16_bf16 v[196:211], v[40:43], v[12:15], v[196:211]
	v_add_f32_e32 v243, v243, v74
	v_add_f32_e32 v243, v243, v75
	v_add_f32_e32 v243, v243, v76
	v_add_f32_e32 v243, v243, v77
	v_cvt_pk_bf16_f32 v110, v72, v73
	v_cvt_pk_bf16_f32 v111, v74, v75
	ds_write_b128 v222, v[108:111] offset:2048
	ds_read_b64_tr_b16 v[128:129], v217 offset:3072
	ds_read_b64_tr_b16 v[130:131], v217 offset:3584
	v_mfma_f32_32x32x16_bf16 v[180:195], v[44:47], v[16:19], v[180:195]
	v_add_f32_e32 v243, v243, v78
	v_add_f32_e32 v243, v243, v79
	v_add_f32_e32 v243, v243, v80
	v_add_f32_e32 v243, v243, v81
	v_cvt_pk_bf16_f32 v112, v76, v77
	v_cvt_pk_bf16_f32 v113, v78, v79
	ds_read_b64_tr_b16 v[144:145], v217 offset:7168
	ds_read_b64_tr_b16 v[146:147], v217 offset:7680
	v_mfma_f32_32x32x16_bf16 v[196:211], v[48:51], v[16:19], v[196:211]
	v_add_f32_e32 v243, v243, v82
	v_add_f32_e32 v243, v243, v83
	v_cvt_pk_bf16_f32 v114, v80, v81
	v_cvt_pk_bf16_f32 v115, v82, v83
	ds_write_b128 v222, v[112:115] offset:3072
	v_add_f32_e32 v213, v213, v243
	s_nop 4
	v_max3_f32 v218, v180, v181, v182
	v_max3_f32 v219, v183, v184, v185
	v_max3_f32 v218, v218, v186, v187
	v_max3_f32 v219, v219, v188, v189
	v_max3_f32 v218, v218, v190, v191
	v_max3_f32 v219, v219, v192, v193
	v_max3_f32 v218, v218, v194, v195
	v_max3_f32 v219, v219, v196, v197
	v_max3_f32 v218, v218, v198, v199
	v_max3_f32 v219, v219, v200, v201
	v_max3_f32 v218, v218, v202, v203
	v_max3_f32 v219, v219, v204, v205
	v_max3_f32 v218, v218, v206, v207
	v_max3_f32 v219, v219, v208, v209
	v_max3_f32 v218, v218, v210, v211
	v_max_f32_e32 v214, v218, v219
	v_mov_b32_e32 v218, v214
	s_nop 1
	v_permlane32_swap_b32_e32 v214, v218
	v_max_f32_e32 v214, v214, v218
	s_mov_b32 s54, 0
	v_mov_b32_e32 v220, 0
	v_cmp_lt_f32_e32 vcc, s48, v214
	s_nop 0
	s_cmp_lg_u64 vcc, 0
	s_cbranch_scc0 .Lat_nores29
	v_max_f32_e32 v214, 0, v214
	v_add_f32_e32 v212, v212, v214
	v_sub_f32_e32 v180, v180, v214
	v_sub_f32_e32 v181, v181, v214
	v_sub_f32_e32 v182, v182, v214
	v_sub_f32_e32 v183, v183, v214
	v_sub_f32_e32 v184, v184, v214
	v_sub_f32_e32 v185, v185, v214
	v_sub_f32_e32 v186, v186, v214
	v_sub_f32_e32 v187, v187, v214
	v_sub_f32_e32 v188, v188, v214
	v_sub_f32_e32 v189, v189, v214
	v_sub_f32_e32 v190, v190, v214
	v_sub_f32_e32 v191, v191, v214
	v_sub_f32_e32 v192, v192, v214
	v_sub_f32_e32 v193, v193, v214
	v_sub_f32_e32 v194, v194, v214
	v_sub_f32_e32 v195, v195, v214
	v_sub_f32_e32 v196, v196, v214
	v_sub_f32_e32 v197, v197, v214
	v_sub_f32_e32 v198, v198, v214
	v_sub_f32_e32 v199, v199, v214
	v_sub_f32_e32 v200, v200, v214
	v_sub_f32_e32 v201, v201, v214
	v_sub_f32_e32 v202, v202, v214
	v_sub_f32_e32 v203, v203, v214
	v_sub_f32_e32 v204, v204, v214
	v_sub_f32_e32 v205, v205, v214
	v_sub_f32_e32 v206, v206, v214
	v_sub_f32_e32 v207, v207, v214
	v_sub_f32_e32 v208, v208, v214
	v_sub_f32_e32 v209, v209, v214
	v_sub_f32_e32 v210, v210, v214
	v_sub_f32_e32 v211, v211, v214
	v_xor_b32_e32 v84, 0x80000000, v212
	v_xor_b32_e32 v85, 0x80000000, v212
	v_xor_b32_e32 v86, 0x80000000, v212
	v_xor_b32_e32 v87, 0x80000000, v212
	v_xor_b32_e32 v88, 0x80000000, v212
	v_xor_b32_e32 v89, 0x80000000, v212
	v_xor_b32_e32 v90, 0x80000000, v212
	v_xor_b32_e32 v91, 0x80000000, v212
	v_xor_b32_e32 v92, 0x80000000, v212
	v_xor_b32_e32 v93, 0x80000000, v212
	v_xor_b32_e32 v94, 0x80000000, v212
	v_xor_b32_e32 v95, 0x80000000, v212
	v_xor_b32_e32 v96, 0x80000000, v212
	v_xor_b32_e32 v97, 0x80000000, v212
	v_xor_b32_e32 v98, 0x80000000, v212
	v_xor_b32_e32 v99, 0x80000000, v212
	v_exp_f32_e64 v215, -v214
	v_mov_b32_e32 v220, 1
	s_mov_b32 s54, 1
	v_mul_f32_e32 v213, v213, v215
	v_add_u32_e32 v221, s44, v235
	v_add_u32_e32 v221, v221, v240
	ds_write_b32 v221, v215
; #define SBAR() __builtin_amdgcn_sched_barrier(0)
;   #define RESC() do{ if(resc){ asm volatile("s_waitcnt lgkmcnt(0)":::"memory"); \
;       _Pragma("unroll") for(int d_=0;d_<2;++d_) _Pragma("unroll") for(int r=0;r<16;++r)o[d_][r]*=wsf[crow(r,hi)]; } }while(0)
;   #define PKW(P,B) cvtpk_s(P[B],P[B+1])
; template<int THRL,bool PART> __device__ __forceinline__ int attn_unit(const bf16*Qb,const bf16*__restrict__ Kh,const bf16*__restrict__ Vh,bf16*Ob,const int NT,const int vlim_in,char*shm,const int s0,const bool primed,const bf16*nKh,const bf16*nVh,bf16*fuseM,const float lam){
;     ...
;   STEP(pB0,pB1,pA0,pA1,NT-1,false,false,false); RESC();
;   if(act){ float sacc=pB0[0]+pB0[1]; _Pragma("unroll") for(int r=2;r<16;++r)sacc+=pB0[r]; _Pragma("unroll") for(int r=0;r<16;++r)sacc+=pB1[r]; l_reg+=sacc;
;     pw0=(u32x4){PKW(pB0,0),PKW(pB0,2),PKW(pB0,4),PKW(pB0,6)};pw1=(u32x4){PKW(pB0,8),PKW(pB0,10),PKW(pB0,12),PKW(pB0,14)};pw2=(u32x4){PKW(pB1,0),PKW(pB1,2),PKW(pB1,4),PKW(pB1,6)};pw3=(u32x4){PKW(pB1,8),PKW(pB1,10),PKW(pB1,12),PKW(pB1,14)};
;     SBAR(); pv(o,vb0+sl_cur,PAF(0),PAF(1),PAF(2),PAF(3)); }
.Lat_nores29:
	v_add_u32_e32 v221, s46, v235
	ds_write_b32 v221, v220 offset:256
	v_add_u32_e32 v216, s26, v232
	s_waitcnt lgkmcnt(2)
	v_mfma_f32_32x32x16_bf16 v[148:163], v[100:103], v[116:119], v[148:163]
	v_exp_f32_e32 v180, v180
	v_exp_f32_e32 v181, v181
	v_exp_f32_e32 v182, v182
	v_exp_f32_e32 v183, v183
	v_mfma_f32_32x32x16_bf16 v[164:179], v[100:103], v[132:135], v[164:179]
	v_exp_f32_e32 v184, v184
	v_exp_f32_e32 v185, v185
	v_exp_f32_e32 v186, v186
	v_exp_f32_e32 v187, v187
	s_add_i32 s34, s17, 1
	s_cmp_lt_u32 s34, s16
	s_cbranch_scc0 .Lat_nokf30
	v_mfma_f32_32x32x16_bf16 v[148:163], v[104:107], v[120:123], v[148:163]
	v_exp_f32_e32 v188, v188
	v_exp_f32_e32 v189, v189
	v_exp_f32_e32 v190, v190
	v_exp_f32_e32 v191, v191
	ds_read_b128 v[20:23], v216 offset:0
	ds_read_b128 v[24:27], v216 offset:512
	v_mfma_f32_32x32x16_bf16 v[164:179], v[104:107], v[136:139], v[164:179]
	v_exp_f32_e32 v192, v192
	v_exp_f32_e32 v193, v193
	v_exp_f32_e32 v194, v194
	v_exp_f32_e32 v195, v195
	ds_read_b128 v[28:31], v216 offset:2048
	ds_read_b128 v[32:35], v216 offset:2560
	v_mfma_f32_32x32x16_bf16 v[148:163], v[108:111], v[124:127], v[148:163]
	v_exp_f32_e32 v196, v196
	v_exp_f32_e32 v197, v197
	v_exp_f32_e32 v198, v198
	v_exp_f32_e32 v199, v199
	ds_read_b128 v[36:39], v216 offset:4096
	ds_read_b128 v[40:43], v216 offset:4608
	v_mfma_f32_32x32x16_bf16 v[164:179], v[108:111], v[140:143], v[164:179]
	v_exp_f32_e32 v200, v200
	v_exp_f32_e32 v201, v201
	v_exp_f32_e32 v202, v202
	v_exp_f32_e32 v203, v203
	ds_read_b128 v[44:47], v216 offset:6144
	ds_read_b128 v[48:51], v216 offset:6656
	v_mfma_f32_32x32x16_bf16 v[148:163], v[112:115], v[128:131], v[148:163]
	v_exp_f32_e32 v204, v204
	v_exp_f32_e32 v205, v205
	v_exp_f32_e32 v206, v206
	v_exp_f32_e32 v207, v207
	v_mfma_f32_32x32x16_bf16 v[164:179], v[112:115], v[144:147], v[164:179]
	v_exp_f32_e32 v208, v208
	v_exp_f32_e32 v209, v209
	v_exp_f32_e32 v210, v210
	v_exp_f32_e32 v211, v211
	s_branch .Lat_Aend28
.Lat_nokf30:
	v_mfma_f32_32x32x16_bf16 v[148:163], v[104:107], v[120:123], v[148:163]
	v_exp_f32_e32 v188, v188
	v_exp_f32_e32 v189, v189
	v_exp_f32_e32 v190, v190
	v_exp_f32_e32 v191, v191
	v_mfma_f32_32x32x16_bf16 v[164:179], v[104:107], v[136:139], v[164:179]
	v_exp_f32_e32 v192, v192
	v_exp_f32_e32 v193, v193
	v_exp_f32_e32 v194, v194
	v_exp_f32_e32 v195, v195
	v_mfma_f32_32x32x16_bf16 v[148:163], v[108:111], v[124:127], v[148:163]
	v_exp_f32_e32 v196, v196
	v_exp_f32_e32 v197, v197
	v_exp_f32_e32 v198, v198
	v_exp_f32_e32 v199, v199
	v_mfma_f32_32x32x16_bf16 v[164:179], v[108:111], v[140:143], v[164:179]
	v_exp_f32_e32 v200, v200
	v_exp_f32_e32 v201, v201
	v_exp_f32_e32 v202, v202
	v_exp_f32_e32 v203, v203
	v_mfma_f32_32x32x16_bf16 v[148:163], v[112:115], v[128:131], v[148:163]
	v_exp_f32_e32 v204, v204
	v_exp_f32_e32 v205, v205
	v_exp_f32_e32 v206, v206
	v_exp_f32_e32 v207, v207
	v_mfma_f32_32x32x16_bf16 v[164:179], v[112:115], v[144:147], v[164:179]
	v_exp_f32_e32 v208, v208
	v_exp_f32_e32 v209, v209
	v_exp_f32_e32 v210, v210
	v_exp_f32_e32 v211, v211
	s_branch .Lat_Aend28
.Lat_Alast27:
	s_mov_b32 s54, 0
	s_cmp_eq_u32 s17, s16
	s_cbranch_scc0 .Lat_Aend28
	v_add_u32_e32 v217, s28, v233
	v_add_u32_e32 v222, s31, v234
	ds_read_b64_tr_b16 v[116:117], v217 offset:0
	ds_read_b64_tr_b16 v[118:119], v217 offset:512
	v_add_f32_e32 v243, v52, v53
	v_add_f32_e32 v243, v243, v54
	v_add_f32_e32 v243, v243, v55
	v_add_f32_e32 v243, v243, v56
	v_add_f32_e32 v243, v243, v57
	v_cvt_pk_bf16_f32 v100, v52, v53
	v_cvt_pk_bf16_f32 v101, v54, v55
	ds_read_b64_tr_b16 v[132:133], v217 offset:4096
	ds_read_b64_tr_b16 v[134:135], v217 offset:4608
	v_add_f32_e32 v243, v243, v58
	v_add_f32_e32 v243, v243, v59
	v_add_f32_e32 v243, v243, v60
	v_add_f32_e32 v243, v243, v61
	v_cvt_pk_bf16_f32 v102, v56, v57
	v_cvt_pk_bf16_f32 v103, v58, v59
	ds_write_b128 v222, v[100:103] offset:0
	ds_read_b64_tr_b16 v[120:121], v217 offset:1024
	ds_read_b64_tr_b16 v[122:123], v217 offset:1536
	v_add_f32_e32 v243, v243, v62
	v_add_f32_e32 v243, v243, v63
	v_add_f32_e32 v243, v243, v64
	v_add_f32_e32 v243, v243, v65
	v_cvt_pk_bf16_f32 v104, v60, v61
	v_cvt_pk_bf16_f32 v105, v62, v63
	ds_read_b64_tr_b16 v[136:137], v217 offset:5120
	ds_read_b64_tr_b16 v[138:139], v217 offset:5632
	v_add_f32_e32 v243, v243, v66
	v_add_f32_e32 v243, v243, v67
	v_add_f32_e32 v243, v243, v68
	v_add_f32_e32 v243, v243, v69
	v_cvt_pk_bf16_f32 v106, v64, v65
	v_cvt_pk_bf16_f32 v107, v66, v67
	ds_write_b128 v222, v[104:107] offset:1024
	ds_read_b64_tr_b16 v[124:125], v217 offset:2048
	ds_read_b64_tr_b16 v[126:127], v217 offset:2560
	v_add_f32_e32 v243, v243, v70
	v_add_f32_e32 v243, v243, v71
	v_add_f32_e32 v243, v243, v72
	v_add_f32_e32 v243, v243, v73
	v_cvt_pk_bf16_f32 v108, v68, v69
	v_cvt_pk_bf16_f32 v109, v70, v71
	ds_read_b64_tr_b16 v[140:141], v217 offset:6144
	ds_read_b64_tr_b16 v[142:143], v217 offset:6656
	v_add_f32_e32 v243, v243, v74
	v_add_f32_e32 v243, v243, v75
	v_add_f32_e32 v243, v243, v76
	v_add_f32_e32 v243, v243, v77
	v_cvt_pk_bf16_f32 v110, v72, v73
	v_cvt_pk_bf16_f32 v111, v74, v75
	ds_write_b128 v222, v[108:111] offset:2048
	ds_read_b64_tr_b16 v[128:129], v217 offset:3072
	ds_read_b64_tr_b16 v[130:131], v217 offset:3584
	v_add_f32_e32 v243, v243, v78
	v_add_f32_e32 v243, v243, v79
	v_add_f32_e32 v243, v243, v80
	v_add_f32_e32 v243, v243, v81
	v_cvt_pk_bf16_f32 v112, v76, v77
	v_cvt_pk_bf16_f32 v113, v78, v79
	ds_read_b64_tr_b16 v[144:145], v217 offset:7168
	ds_read_b64_tr_b16 v[146:147], v217 offset:7680
	v_add_f32_e32 v243, v243, v82
	v_add_f32_e32 v243, v243, v83
	v_cvt_pk_bf16_f32 v114, v80, v81
	v_cvt_pk_bf16_f32 v115, v82, v83
	ds_write_b128 v222, v[112:115] offset:3072
	v_add_f32_e32 v213, v213, v243
	v_mov_b32_e32 v220, 0
	v_add_u32_e32 v221, s46, v235
	ds_write_b32 v221, v220 offset:256
	s_waitcnt lgkmcnt(2)
	v_mfma_f32_32x32x16_bf16 v[148:163], v[100:103], v[116:119], v[148:163]
	v_mfma_f32_32x32x16_bf16 v[164:179], v[100:103], v[132:135], v[164:179]
	v_mfma_f32_32x32x16_bf16 v[148:163], v[104:107], v[120:123], v[148:163]
	v_mfma_f32_32x32x16_bf16 v[164:179], v[104:107], v[136:139], v[164:179]
	v_mfma_f32_32x32x16_bf16 v[148:163], v[108:111], v[124:127], v[148:163]
	v_mfma_f32_32x32x16_bf16 v[164:179], v[108:111], v[140:143], v[164:179]
	v_mfma_f32_32x32x16_bf16 v[148:163], v[112:115], v[128:131], v[148:163]
	v_mfma_f32_32x32x16_bf16 v[164:179], v[112:115], v[144:147], v[164:179]

; __device__ __forceinline__ int crow(int r,int hi){return (r&3)+8*(r>>2)+4*hi;}
; template<int THRL,bool PART> __device__ __forceinline__ int attn_unit(const bf16*Qb,const bf16*__restrict__ Kh,const bf16*__restrict__ Vh,bf16*Ob,const int NT,const int vlim_in,char*shm,const int s0,const bool primed,const bf16*nKh,const bf16*nVh,bf16*fuseM,const float lam){
;     ...
;   if(act){
;   {auto rr=__builtin_amdgcn_permlane32_swap(__float_as_uint(l_reg),__float_as_uint(l_reg),false,false);l_reg=__uint_as_float(rr[0])+__uint_as_float(rr[1]);}
;   if(hi==0)wsf[32+r32]=l_reg;asm volatile("s_waitcnt lgkmcnt(0)":::"memory");
;   float rli[16];
;   #pragma unroll
;   for(int r=0;r<16;++r)rli[r]=__builtin_amdgcn_rcpf(wsf[32+crow(r,hi)]);
.Lat_bar24:
	s_barrier
	s_add_i32 s24, s24, 1
	s_cmp_eq_u32 s24, 3
	s_cselect_b32 s24, 0, s24
	s_add_i32 s25, s25, 1
	s_and_b32 s25, s25, 3
	s_add_i32 s17, s17, 1
	s_add_i32 s34, s15, 1
	s_cmp_le_u32 s17, s34
	s_cbranch_scc1 .Lat_t5
.Lat_tx6:
	s_cmp_lg_u32 s6, 0
	s_cbranch_scc1 .Lat_eB36
	v_mov_b32_e32 v218, v213
	s_nop 1
	v_permlane32_swap_b32_e32 v213, v218
	v_add_f32_e32 v213, v213, v218
	v_rcp_f32_e32 v213, v213
	v_add_u32_e32 v221, v235, v240
	s_nop 0
	ds_write_b32 v221, v213 offset:384
.Lat_eB36:
	s_waitcnt lgkmcnt(0)
	s_barrier
	v_add_u32_e32 v221, v235, v241
	ds_read_b128 v[116:119], v221 offset:384
	ds_read_b128 v[120:123], v221 offset:416
	ds_read_b128 v[124:127], v221 offset:448
	ds_read_b128 v[128:131], v221 offset:480
	s_waitcnt lgkmcnt(0)
	s_nop 7
	s_nop 3
	v_mul_f32_e32 v148, v148, v116
	v_mul_f32_e32 v149, v149, v117
	v_mul_f32_e32 v150, v150, v118
	v_mul_f32_e32 v151, v151, v119
	v_mul_f32_e32 v152, v152, v120
	v_mul_f32_e32 v153, v153, v121
	v_mul_f32_e32 v154, v154, v122
	v_mul_f32_e32 v155, v155, v123
	v_mul_f32_e32 v156, v156, v124
	v_mul_f32_e32 v157, v157, v125
	v_mul_f32_e32 v158, v158, v126
	v_mul_f32_e32 v159, v159, v127
	v_mul_f32_e32 v160, v160, v128
	v_mul_f32_e32 v161, v161, v129
	v_mul_f32_e32 v162, v162, v130
	v_mul_f32_e32 v163, v163, v131
	v_mul_f32_e32 v164, v164, v116
	v_mul_f32_e32 v165, v165, v117
	v_mul_f32_e32 v166, v166, v118
	v_mul_f32_e32 v167, v167, v119
	v_mul_f32_e32 v168, v168, v120
	v_mul_f32_e32 v169, v169, v121
	v_mul_f32_e32 v170, v170, v122
	v_mul_f32_e32 v171, v171, v123
	v_mul_f32_e32 v172, v172, v124
	v_mul_f32_e32 v173, v173, v125
	v_mul_f32_e32 v174, v174, v126
	v_mul_f32_e32 v175, v175, v127
	v_mul_f32_e32 v176, v176, v128
	v_mul_f32_e32 v177, v177, v129
	v_mul_f32_e32 v178, v178, v130
	v_mul_f32_e32 v179, v179, v131
	s_cmp_lg_u32 s14, 0
	s_cbranch_scc1 .Lat_comb37
	global_store_dwordx4 v242, v[148:151], s[52:53]
	global_store_dwordx4 v242, v[152:155], s[52:53] offset:1024
	global_store_dwordx4 v242, v[156:159], s[52:53] offset:2048
	global_store_dwordx4 v242, v[160:163], s[52:53] offset:3072
	global_store_dwordx4 v244, v[164:167], s[52:53]
	global_store_dwordx4 v244, v[168:171], s[52:53] offset:1024
	global_store_dwordx4 v244, v[172:175], s[52:53] offset:2048
	global_store_dwordx4 v244, v[176:179], s[52:53] offset:3072
	s_branch .Lat_udone38
; __device__ __forceinline__ unsigned cvtpk_s(float lo,float hi){f32x2_t v={lo,hi};bf16x2_t b=__builtin_convertvector(v,bf16x2_t);return __builtin_bit_cast(unsigned,b);}
; template<int THRL,bool PART> __device__ __forceinline__ int attn_unit(const bf16*Qb,const bf16*__restrict__ Kh,const bf16*__restrict__ Vh,bf16*Ob,const int NT,const int vlim_in,char*shm,const int s0,const bool primed,const bf16*nKh,const bf16*nVh,bf16*fuseM,const float lam){
;     ...
;     asm volatile("s_waitcnt vmcnt(0)":::"memory"); __builtin_amdgcn_fence(__ATOMIC_ACQUIRE,"agent");
;     bf16*Mw=fuseM+(long)(wid*QBLK)*OP;
;     #pragma unroll
;     for(int i=0;i<4;++i){const int row=i*8+(lane>>3),ch=lane&7; const u32x4 v=*(const u32x4*)(stg+row*64+ch*8);
;       const bf16*gp=Ow+(long)row*OP+ch*8; const u32x4 a=*(const u32x4*)(gp-192), c1=*(const u32x4*)(gp-128), b=*(const u32x4*)(gp-64);
;       float d0[8],d1[8],ss=0.f;
;       #pragma unroll
;       for(int q=0;q<4;++q){ d0[2*q]=__uint_as_float(a[q]<<16)-lam*__uint_as_float(b[q]<<16); d0[2*q+1]=__uint_as_float(a[q]&0xffff0000u)-lam*__uint_as_float(b[q]&0xffff0000u);
;         d1[2*q]=__uint_as_float(c1[q]<<16)-lam*__uint_as_float(v[q]<<16); d1[2*q+1]=__uint_as_float(c1[q]&0xffff0000u)-lam*__uint_as_float(v[q]&0xffff0000u);
;         ss+=d0[2*q]*d0[2*q]+d0[2*q+1]*d0[2*q+1]+d1[2*q]*d1[2*q]+d1[2*q+1]*d1[2*q+1]; }
;       ss+=__shfl_xor(ss,1); ss+=__shfl_xor(ss,2); ss+=__shfl_xor(ss,4);
;       const float rn=rsqrtf(ss*(1.0f/128.0f)+1e-6f)*0.8f;
;       u32x4 w0,w1;
;       #pragma unroll
;       for(int q=0;q<4;++q){ w0[q]=cvtpk_s(d0[2*q]*rn,d0[2*q+1]*rn); w1[q]=cvtpk_s(d1[2*q]*rn,d1[2*q+1]*rn); }
;       *(u32x4*)(Mw+(long)row*OP+ch*8)=w0; *(u32x4*)(Mw+(long)row*OP+64+ch*8)=w1; }
;     } }
.Lat_comb37:
	global_load_dwordx4 v[52:55], v242, s[52:53] sc1
	global_load_dwordx4 v[56:59], v242, s[52:53] offset:1024 sc1
	global_load_dwordx4 v[60:63], v242, s[52:53] offset:2048 sc1
	global_load_dwordx4 v[64:67], v242, s[52:53] offset:3072 sc1
	global_load_dwordx4 v[68:71], v244, s[52:53] sc1
	global_load_dwordx4 v[72:75], v244, s[52:53] offset:1024 sc1
	global_load_dwordx4 v[76:79], v244, s[52:53] offset:2048 sc1
	global_load_dwordx4 v[80:83], v244, s[52:53] offset:3072 sc1
	v_mov_b32_e32 v218, s7
	s_mul_i32 s34, s5, 0x4200
	s_lshl_b32 s35, s6, 8
	s_add_i32 s34, s34, s35
	v_mul_u32_u24_e32 v221, 0x840, v2
	v_add_u32_e32 v221, v221, v240
	v_add_u32_e32 v221, s34, v221
	s_waitcnt vmcnt(0)
	v_fma_f32 v52, -v218, v148, v52
	v_fma_f32 v53, -v218, v149, v53
	v_fma_f32 v54, -v218, v150, v54
	v_fma_f32 v55, -v218, v151, v55
	v_fma_f32 v56, -v218, v152, v56
	v_fma_f32 v57, -v218, v153, v57
	v_fma_f32 v58, -v218, v154, v58
	v_fma_f32 v59, -v218, v155, v59
	v_fma_f32 v60, -v218, v156, v60
	v_fma_f32 v61, -v218, v157, v61
	v_fma_f32 v62, -v218, v158, v62
	v_fma_f32 v63, -v218, v159, v63
	v_fma_f32 v64, -v218, v160, v64
	v_fma_f32 v65, -v218, v161, v65
	v_fma_f32 v66, -v218, v162, v66
	v_fma_f32 v67, -v218, v163, v67
	v_fma_f32 v68, -v218, v164, v68
	v_fma_f32 v69, -v218, v165, v69
	v_fma_f32 v70, -v218, v166, v70
	v_fma_f32 v71, -v218, v167, v71
	v_fma_f32 v72, -v218, v168, v72
	v_fma_f32 v73, -v218, v169, v73
	v_fma_f32 v74, -v218, v170, v74
	v_fma_f32 v75, -v218, v171, v75
	v_fma_f32 v76, -v218, v172, v76
	v_fma_f32 v77, -v218, v173, v77
	v_fma_f32 v78, -v218, v174, v78
	v_fma_f32 v79, -v218, v175, v79
	v_fma_f32 v80, -v218, v176, v80
	v_fma_f32 v81, -v218, v177, v81
	v_fma_f32 v82, -v218, v178, v82
	v_fma_f32 v83, -v218, v179, v83
	ds_write_b32 v221, v52 offset:0
	ds_write_b32 v221, v53 offset:528
	ds_write_b32 v221, v54 offset:1056
	ds_write_b32 v221, v55 offset:1584
	ds_write_b32 v221, v56 offset:4224
	ds_write_b32 v221, v57 offset:4752
	ds_write_b32 v221, v58 offset:5280
	ds_write_b32 v221, v59 offset:5808
	ds_write_b32 v221, v60 offset:8448
	ds_write_b32 v221, v61 offset:8976
	ds_write_b32 v221, v62 offset:9504
	ds_write_b32 v221, v63 offset:10032
	ds_write_b32 v221, v64 offset:12672
	ds_write_b32 v221, v65 offset:13200
	ds_write_b32 v221, v66 offset:13728
	ds_write_b32 v221, v67 offset:14256
	ds_write_b32 v221, v68 offset:128
	ds_write_b32 v221, v69 offset:656
	ds_write_b32 v221, v70 offset:1184
	ds_write_b32 v221, v71 offset:1712
	ds_write_b32 v221, v72 offset:4352
	ds_write_b32 v221, v73 offset:4880
	ds_write_b32 v221, v74 offset:5408
	ds_write_b32 v221, v75 offset:5936
	ds_write_b32 v221, v76 offset:8576
	ds_write_b32 v221, v77 offset:9104
	ds_write_b32 v221, v78 offset:9632
	ds_write_b32 v221, v79 offset:10160
	ds_write_b32 v221, v80 offset:12800
	ds_write_b32 v221, v81 offset:13328
	ds_write_b32 v221, v82 offset:13856
	ds_write_b32 v221, v83 offset:14384
	s_waitcnt lgkmcnt(0)
	s_barrier
	v_lshrrev_b32_e32 v222, 2, v252
	v_and_b32_e32 v223, 3, v252
	v_mul_u32_u24_e32 v221, 0x210, v222
	v_lshl_add_u32 v221, v223, 7, v221
	ds_read_b128 v[52:55], v221 offset:0
	ds_read_b128 v[56:59], v221 offset:16
	ds_read_b128 v[60:63], v221 offset:32
	ds_read_b128 v[64:67], v221 offset:48
	ds_read_b128 v[68:71], v221 offset:64
	ds_read_b128 v[72:75], v221 offset:80
	ds_read_b128 v[76:79], v221 offset:96
	ds_read_b128 v[80:83], v221 offset:112
	s_waitcnt lgkmcnt(0)
	v_mul_f32_e32 v218, v52, v52
	v_fmac_f32_e32 v218, v53, v53
	v_fmac_f32_e32 v218, v54, v54
	v_fmac_f32_e32 v218, v55, v55
	v_fmac_f32_e32 v218, v56, v56
	v_fmac_f32_e32 v218, v57, v57
	v_fmac_f32_e32 v218, v58, v58
	v_fmac_f32_e32 v218, v59, v59
	v_fmac_f32_e32 v218, v60, v60
	v_fmac_f32_e32 v218, v61, v61
	v_fmac_f32_e32 v218, v62, v62
	v_fmac_f32_e32 v218, v63, v63
	v_fmac_f32_e32 v218, v64, v64
	v_fmac_f32_e32 v218, v65, v65
	v_fmac_f32_e32 v218, v66, v66
	v_fmac_f32_e32 v218, v67, v67
	v_fmac_f32_e32 v218, v68, v68
	v_fmac_f32_e32 v218, v69, v69
	v_fmac_f32_e32 v218, v70, v70
	v_fmac_f32_e32 v218, v71, v71
	v_fmac_f32_e32 v218, v72, v72
	v_fmac_f32_e32 v218, v73, v73
	v_fmac_f32_e32 v218, v74, v74
	v_fmac_f32_e32 v218, v75, v75
	v_fmac_f32_e32 v218, v76, v76
	v_fmac_f32_e32 v218, v77, v77
	v_fmac_f32_e32 v218, v78, v78
	v_fmac_f32_e32 v218, v79, v79
	v_fmac_f32_e32 v218, v80, v80
	v_fmac_f32_e32 v218, v81, v81
	v_fmac_f32_e32 v218, v82, v82
	v_fmac_f32_e32 v218, v83, v83
	s_nop 1
	v_add_f32_dpp v218, v218, v218 quad_perm:[1,0,3,2] row_mask:0xf bank_mask:0xf
	s_nop 1
	v_add_f32_dpp v218, v218, v218 quad_perm:[2,3,0,1] row_mask:0xf bank_mask:0xf
	v_mov_b32_e32 v219, 0x358637bd
	v_fmamk_f32 v218, v218, 0x3c000000, v219
	v_rsq_f32_e32 v218, v218
	s_nop 0
	v_mul_f32_e32 v218, 0x3f4ccccd, v218
	v_mul_f32_e32 v52, v52, v218
	v_mul_f32_e32 v53, v53, v218
	v_mul_f32_e32 v54, v54, v218
	v_mul_f32_e32 v55, v55, v218
	v_mul_f32_e32 v56, v56, v218
	v_mul_f32_e32 v57, v57, v218
	v_mul_f32_e32 v58, v58, v218
	v_mul_f32_e32 v59, v59, v218
	v_mul_f32_e32 v60, v60, v218
	v_mul_f32_e32 v61, v61, v218
	v_mul_f32_e32 v62, v62, v218
	v_mul_f32_e32 v63, v63, v218
	v_mul_f32_e32 v64, v64, v218
	v_mul_f32_e32 v65, v65, v218
	v_mul_f32_e32 v66, v66, v218
	v_mul_f32_e32 v67, v67, v218
	v_mul_f32_e32 v68, v68, v218
	v_mul_f32_e32 v69, v69, v218
	v_mul_f32_e32 v70, v70, v218
	v_mul_f32_e32 v71, v71, v218
	v_mul_f32_e32 v72, v72, v218
	v_mul_f32_e32 v73, v73, v218
	v_mul_f32_e32 v74, v74, v218
	v_mul_f32_e32 v75, v75, v218
	v_mul_f32_e32 v76, v76, v218
	v_mul_f32_e32 v77, v77, v218
	v_mul_f32_e32 v78, v78, v218
	v_mul_f32_e32 v79, v79, v218
	v_mul_f32_e32 v80, v80, v218
	v_mul_f32_e32 v81, v81, v218
	v_mul_f32_e32 v82, v82, v218
	v_mul_f32_e32 v83, v83, v218
	v_cvt_pk_bf16_f32 v100, v52, v53
	v_cvt_pk_bf16_f32 v101, v54, v55
	v_cvt_pk_bf16_f32 v102, v56, v57
	v_cvt_pk_bf16_f32 v103, v58, v59
	v_cvt_pk_bf16_f32 v104, v60, v61
	v_cvt_pk_bf16_f32 v105, v62, v63
	v_cvt_pk_bf16_f32 v106, v64, v65
	v_cvt_pk_bf16_f32 v107, v66, v67
	v_cvt_pk_bf16_f32 v108, v68, v69
	v_cvt_pk_bf16_f32 v109, v70, v71
	v_cvt_pk_bf16_f32 v110, v72, v73
	v_cvt_pk_bf16_f32 v111, v74, v75
	v_cvt_pk_bf16_f32 v112, v76, v77
	v_cvt_pk_bf16_f32 v113, v78, v79
	v_cvt_pk_bf16_f32 v114, v80, v81
	v_cvt_pk_bf16_f32 v115, v82, v83
	s_add_u32 s50, s66, 0x2e00400
	s_addc_u32 s51, s67, 0
	s_lshl_b32 s36, s9, 23
	s_add_u32 s50, s50, s36
	s_addc_u32 s51, s51, 0
	s_lshl_b32 s36, s13, 18
	s_add_u32 s50, s50, s36
	s_addc_u32 s51, s51, 0
	s_lshl_b32 s36, s10, 8
	s_add_u32 s50, s50, s36
	s_addc_u32 s51, s51, 0
	v_lshlrev_b32_e32 v221, 11, v222
	v_lshl_add_u32 v221, v223, 6, v221
	global_store_dwordx4 v221, v[100:103], s[50:51]
	global_store_dwordx4 v221, v[104:107], s[50:51] offset:16
	global_store_dwordx4 v221, v[108:111], s[50:51] offset:32
	global_store_dwordx4 v221, v[112:115], s[50:51] offset:48
